# grid barrier: every XCD leader adds to all per-XCC generation words right after its write-back (no returning top arrival, no last-leader detection); waiters wait for word >= 1 + gen*nx
# speedup vs baseline: 1.0077x; 1.0077x over previous
.LBB0_300:
	s_or_b64 exec, exec, s[6:7]
	v_cvt_f32_u32_e32 v4, v2
	s_waitcnt vmcnt(0)
	v_readfirstlane_b32 s4, v3
	v_sub_u32_e32 v3, 0, v2
	v_rcp_iflag_f32_e32 v4, v4
	v_add_u32_e32 v5, s4, v1
	v_mul_f32_e32 v4, 0x4f7ffffe, v4
	v_cvt_u32_f32_e32 v4, v4
	v_mul_lo_u32 v1, v3, v4
	v_mul_hi_u32 v1, v4, v1
	v_add_u32_e32 v1, v4, v1
	v_mul_hi_u32 v1, v5, v1
	v_mul_lo_u32 v3, v1, v2
	v_sub_u32_e32 v3, v5, v3
	v_add_u32_e32 v4, 1, v1
	v_cmp_ge_u32_e32 vcc, v3, v2
	s_nop 1
	v_cndmask_b32_e32 v1, v1, v4, vcc
	v_sub_u32_e32 v4, v3, v2
	v_cndmask_b32_e32 v3, v3, v4, vcc
	v_add_u32_e32 v4, 1, v1
	v_cmp_ge_u32_e32 vcc, v3, v2
	v_add_u32_e32 v3, 1, v5
	s_nop 0
	v_cndmask_b32_e32 v1, v1, v4, vcc
	v_mul_lo_u32 v4, v2, v1
	v_add_u32_e32 v2, v4, v2
	v_cmp_ne_u32_e32 vcc, v3, v2
	s_and_saveexec_b64 s[4:5], vcc
	s_xor_b64 s[4:5], exec, s[4:5]
	s_cbranch_execz .LBB0_314
	s_add_i32 s48, s30, 0x900
	s_lshl_b64 s[6:7], s[48:49], 2
	s_add_u32 s8, s2, s6
	s_addc_u32 s9, s3, s7
	s_waitcnt lgkmcnt(0)
	v_mad_u32_u24 v1, v1, v0, 1
	global_load_dword v0, v149, s[8:9] sc1
	s_waitcnt vmcnt(0)
	v_cmp_lt_u32_e32 vcc, v0, v1
	s_and_saveexec_b64 s[6:7], vcc
	s_cbranch_execz .LBB0_313
	s_mov_b32 s26, 1
	s_mov_b64 s[10:11], 0
	s_branch .LBB0_304

.LBB0_308:
	global_load_dword v0, v149, s[8:9] sc1
	s_add_i32 s26, s26, 1
	s_mov_b64 s[22:23], -1
	s_waitcnt vmcnt(0)
	v_cmp_ge_u32_e32 vcc, v0, v1
	s_orn2_b64 s[20:21], vcc, exec
	s_branch .LBB0_303

.LBB0_314:
	s_andn2_saveexec_b64 s[4:5], s[4:5]
	s_cbranch_execz .LBB0_334
	s_mov_b64 s[4:5], exec
	buffer_wbl2 sc1
	s_waitcnt lgkmcnt(0)
	s_waitcnt vmcnt(0)
	v_mad_u32_u24 v2, v1, v0, 1
	s_add_u32 s10, s2, 0x2400
	s_addc_u32 s11, s3, 0
	global_atomic_add v149, v211, s[10:11]
	global_atomic_add v149, v211, s[10:11] offset:256
	global_atomic_add v149, v211, s[10:11] offset:512
	global_atomic_add v149, v211, s[10:11] offset:768
	global_atomic_add v149, v211, s[10:11] offset:1024
	global_atomic_add v149, v211, s[10:11] offset:1280
	global_atomic_add v149, v211, s[10:11] offset:1536
	global_atomic_add v149, v211, s[10:11] offset:1792
	global_atomic_add v149, v211, s[10:11] offset:2048
	global_atomic_add v149, v211, s[10:11] offset:2304
	global_atomic_add v149, v211, s[10:11] offset:2560
	global_atomic_add v149, v211, s[10:11] offset:2816
	global_atomic_add v149, v211, s[10:11] offset:3072
	global_atomic_add v149, v211, s[10:11] offset:3328
	global_atomic_add v149, v211, s[10:11] offset:3584
	global_atomic_add v149, v211, s[10:11] offset:3840
	s_lshl_b32 s4, s30, 2
	s_add_u32 s4, s2, s4
	s_addc_u32 s5, s3, 0
	s_add_u32 s4, s4, 0x2400
	s_addc_u32 s5, s5, 0
	v_mov_b64_e32 v[0:1], s[4:5]
	s_mov_b64 s[6:7], exec
.Lgs_poll_0:
	global_load_dword v0, v149, s[4:5] sc1
	s_mov_b64 s[18:19], 0
	s_waitcnt vmcnt(0)
	v_cmp_lt_u32_e32 vcc, v0, v2
	s_and_saveexec_b64 s[10:11], vcc
	s_cbranch_execz .LBB0_328
	s_add_u32 s8, s2, 0x200
	s_addc_u32 s9, s3, 0
	s_mov_b32 s31, 1
	s_branch .LBB0_321

.LBB0_325:
	global_load_dword v0, v149, s[4:5] sc1
	s_add_i32 s31, s31, 1
	s_mov_b64 s[24:25], -1
	s_waitcnt vmcnt(0)
	v_cmp_ge_u32_e32 vcc, v0, v2
	s_orn2_b64 s[22:23], vcc, exec
	s_branch .LBB0_320

.LBB0_545:
	s_or_b64 exec, exec, s[6:7]
	v_cvt_f32_u32_e32 v4, v2
	s_waitcnt vmcnt(0)
	v_readfirstlane_b32 s4, v3
	v_sub_u32_e32 v3, 0, v2
	v_rcp_iflag_f32_e32 v4, v4
	v_add_u32_e32 v5, s4, v1
	v_mul_f32_e32 v4, 0x4f7ffffe, v4
	v_cvt_u32_f32_e32 v4, v4
	v_mul_lo_u32 v1, v3, v4
	v_mul_hi_u32 v1, v4, v1
	v_add_u32_e32 v1, v4, v1
	v_mul_hi_u32 v1, v5, v1
	v_mul_lo_u32 v3, v1, v2
	v_sub_u32_e32 v3, v5, v3
	v_add_u32_e32 v4, 1, v1
	v_cmp_ge_u32_e32 vcc, v3, v2
	s_nop 1
	v_cndmask_b32_e32 v1, v1, v4, vcc
	v_sub_u32_e32 v4, v3, v2
	v_cndmask_b32_e32 v3, v3, v4, vcc
	v_add_u32_e32 v4, 1, v1
	v_cmp_ge_u32_e32 vcc, v3, v2
	v_add_u32_e32 v3, 1, v5
	s_nop 0
	v_cndmask_b32_e32 v1, v1, v4, vcc
	v_mul_lo_u32 v4, v2, v1
	v_add_u32_e32 v2, v4, v2
	v_cmp_ne_u32_e32 vcc, v3, v2
	s_and_saveexec_b64 s[4:5], vcc
	s_xor_b64 s[4:5], exec, s[4:5]
	s_cbranch_execz .LBB0_559
	s_add_i32 s48, s22, 0x900
	s_lshl_b64 s[6:7], s[48:49], 2
	s_add_u32 s8, s2, s6
	s_addc_u32 s9, s3, s7
	s_waitcnt lgkmcnt(0)
	v_mad_u32_u24 v1, v1, v0, 1
	global_load_dword v0, v149, s[8:9] sc1
	s_waitcnt vmcnt(0)
	v_cmp_lt_u32_e32 vcc, v0, v1
	s_and_saveexec_b64 s[6:7], vcc
	s_cbranch_execz .LBB0_558
	s_mov_b32 s20, 1
	s_mov_b64 s[10:11], 0
	s_branch .LBB0_549

.LBB0_553:
	global_load_dword v0, v149, s[8:9] sc1
	s_add_i32 s20, s20, 1
	s_mov_b64 s[16:17], -1
	s_waitcnt vmcnt(0)
	v_cmp_ge_u32_e32 vcc, v0, v1
	s_orn2_b64 s[14:15], vcc, exec
	s_branch .LBB0_548

.LBB0_559:
	s_andn2_saveexec_b64 s[4:5], s[4:5]
	s_cbranch_execz .LBB0_579
	s_mov_b64 s[4:5], exec
	buffer_wbl2 sc1
	s_waitcnt lgkmcnt(0)
	s_waitcnt vmcnt(0)
	v_mad_u32_u24 v2, v1, v0, 1
	s_add_u32 s10, s2, 0x2400
	s_addc_u32 s11, s3, 0
	global_atomic_add v149, v211, s[10:11]
	global_atomic_add v149, v211, s[10:11] offset:256
	global_atomic_add v149, v211, s[10:11] offset:512
	global_atomic_add v149, v211, s[10:11] offset:768
	global_atomic_add v149, v211, s[10:11] offset:1024
	global_atomic_add v149, v211, s[10:11] offset:1280
	global_atomic_add v149, v211, s[10:11] offset:1536
	global_atomic_add v149, v211, s[10:11] offset:1792
	global_atomic_add v149, v211, s[10:11] offset:2048
	global_atomic_add v149, v211, s[10:11] offset:2304
	global_atomic_add v149, v211, s[10:11] offset:2560
	global_atomic_add v149, v211, s[10:11] offset:2816
	global_atomic_add v149, v211, s[10:11] offset:3072
	global_atomic_add v149, v211, s[10:11] offset:3328
	global_atomic_add v149, v211, s[10:11] offset:3584
	global_atomic_add v149, v211, s[10:11] offset:3840
	s_lshl_b32 s4, s22, 2
	s_add_u32 s4, s2, s4
	s_addc_u32 s5, s3, 0
	s_add_u32 s4, s4, 0x2400
	s_addc_u32 s5, s5, 0
	v_mov_b64_e32 v[0:1], s[4:5]
	s_mov_b64 s[6:7], exec
.Lgs_poll_1:
	global_load_dword v0, v149, s[4:5] sc1
	s_mov_b64 s[12:13], 0
	s_waitcnt vmcnt(0)
	v_cmp_lt_u32_e32 vcc, v0, v2
	s_and_saveexec_b64 s[10:11], vcc
	s_cbranch_execz .LBB0_573
	s_add_u32 s8, s2, 0x200
	s_addc_u32 s9, s3, 0
	s_mov_b32 s23, 1
	s_branch .LBB0_566

.LBB0_570:
	global_load_dword v0, v149, s[4:5] sc1
	s_add_i32 s23, s23, 1
	s_mov_b64 s[18:19], -1
	s_waitcnt vmcnt(0)
	v_cmp_ge_u32_e32 vcc, v0, v2
	s_orn2_b64 s[16:17], vcc, exec
	s_branch .LBB0_565

.LBB0_798:
	s_or_b64 exec, exec, s[8:9]
	v_cvt_f32_u32_e32 v4, v2
	s_waitcnt vmcnt(0)
	v_readfirstlane_b32 s4, v3
	v_sub_u32_e32 v3, 0, v2
	v_rcp_iflag_f32_e32 v4, v4
	v_add_u32_e32 v5, s4, v1
	v_mul_f32_e32 v4, 0x4f7ffffe, v4
	v_cvt_u32_f32_e32 v4, v4
	v_mul_lo_u32 v1, v3, v4
	v_mul_hi_u32 v1, v4, v1
	v_add_u32_e32 v1, v4, v1
	v_mul_hi_u32 v1, v5, v1
	v_mul_lo_u32 v3, v1, v2
	v_sub_u32_e32 v3, v5, v3
	v_add_u32_e32 v4, 1, v1
	v_cmp_ge_u32_e32 vcc, v3, v2
	s_nop 1
	v_cndmask_b32_e32 v1, v1, v4, vcc
	v_sub_u32_e32 v4, v3, v2
	v_cndmask_b32_e32 v3, v3, v4, vcc
	v_add_u32_e32 v4, 1, v1
	v_cmp_ge_u32_e32 vcc, v3, v2
	v_add_u32_e32 v3, 1, v5
	s_nop 0
	v_cndmask_b32_e32 v1, v1, v4, vcc
	v_mul_lo_u32 v4, v2, v1
	v_add_u32_e32 v2, v4, v2
	v_cmp_ne_u32_e32 vcc, v3, v2
	s_and_saveexec_b64 s[4:5], vcc
	s_xor_b64 s[4:5], exec, s[4:5]
	s_cbranch_execz .LBB0_812
	s_add_i32 s48, s24, 0x900
	s_lshl_b64 s[8:9], s[48:49], 2
	s_add_u32 s10, s2, s8
	s_addc_u32 s11, s3, s9
	s_waitcnt lgkmcnt(0)
	v_mad_u32_u24 v1, v1, v0, 1
	global_load_dword v0, v149, s[10:11] sc1
	s_waitcnt vmcnt(0)
	v_cmp_lt_u32_e32 vcc, v0, v1
	s_and_saveexec_b64 s[8:9], vcc
	s_cbranch_execz .LBB0_811
	s_mov_b32 s22, 1
	s_mov_b64 s[12:13], 0
	s_branch .LBB0_802

.LBB0_806:
	global_load_dword v0, v149, s[10:11] sc1
	s_add_i32 s22, s22, 1
	s_mov_b64 s[18:19], -1
	s_waitcnt vmcnt(0)
	v_cmp_ge_u32_e32 vcc, v0, v1
	s_orn2_b64 s[16:17], vcc, exec
	s_branch .LBB0_801

.LBB0_812:
	s_andn2_saveexec_b64 s[4:5], s[4:5]
	s_cbranch_execz .LBB0_832
	s_mov_b64 s[4:5], exec
	buffer_wbl2 sc1
	s_waitcnt lgkmcnt(0)
	s_waitcnt vmcnt(0)
	v_mad_u32_u24 v2, v1, v0, 1
	s_add_u32 s12, s2, 0x2400
	s_addc_u32 s13, s3, 0
	global_atomic_add v149, v211, s[12:13]
	global_atomic_add v149, v211, s[12:13] offset:256
	global_atomic_add v149, v211, s[12:13] offset:512
	global_atomic_add v149, v211, s[12:13] offset:768
	global_atomic_add v149, v211, s[12:13] offset:1024
	global_atomic_add v149, v211, s[12:13] offset:1280
	global_atomic_add v149, v211, s[12:13] offset:1536
	global_atomic_add v149, v211, s[12:13] offset:1792
	global_atomic_add v149, v211, s[12:13] offset:2048
	global_atomic_add v149, v211, s[12:13] offset:2304
	global_atomic_add v149, v211, s[12:13] offset:2560
	global_atomic_add v149, v211, s[12:13] offset:2816
	global_atomic_add v149, v211, s[12:13] offset:3072
	global_atomic_add v149, v211, s[12:13] offset:3328
	global_atomic_add v149, v211, s[12:13] offset:3584
	global_atomic_add v149, v211, s[12:13] offset:3840
	s_lshl_b32 s4, s24, 2
	s_add_u32 s4, s2, s4
	s_addc_u32 s5, s3, 0
	s_add_u32 s4, s4, 0x2400
	s_addc_u32 s5, s5, 0
	v_mov_b64_e32 v[0:1], s[4:5]
	s_mov_b64 s[8:9], exec
.Lgs_poll_2:
	global_load_dword v0, v149, s[4:5] sc1
	s_mov_b64 s[14:15], 0
	s_waitcnt vmcnt(0)
	v_cmp_lt_u32_e32 vcc, v0, v2
	s_and_saveexec_b64 s[12:13], vcc
	s_cbranch_execz .LBB0_826
	s_add_u32 s10, s2, 0x200
	s_addc_u32 s11, s3, 0
	s_mov_b32 s25, 1
	s_branch .LBB0_819

.LBB0_823:
	global_load_dword v0, v149, s[4:5] sc1
	s_add_i32 s25, s25, 1
	s_mov_b64 s[20:21], -1
	s_waitcnt vmcnt(0)
	v_cmp_ge_u32_e32 vcc, v0, v2
	s_orn2_b64 s[18:19], vcc, exec
	s_branch .LBB0_818

.LBB0_1494:
	s_mov_b64 s[4:5], exec
	buffer_wbl2 sc1
	s_waitcnt lgkmcnt(0)
	s_waitcnt vmcnt(0)
	v_mad_u32_u24 v2, v1, v0, 1
	s_add_u32 s10, s2, 0x2400
	s_addc_u32 s11, s3, 0
	global_atomic_add v149, v211, s[10:11]
	global_atomic_add v149, v211, s[10:11] offset:256
	global_atomic_add v149, v211, s[10:11] offset:512
	global_atomic_add v149, v211, s[10:11] offset:768
	global_atomic_add v149, v211, s[10:11] offset:1024
	global_atomic_add v149, v211, s[10:11] offset:1280
	global_atomic_add v149, v211, s[10:11] offset:1536
	global_atomic_add v149, v211, s[10:11] offset:1792
	global_atomic_add v149, v211, s[10:11] offset:2048
	global_atomic_add v149, v211, s[10:11] offset:2304
	global_atomic_add v149, v211, s[10:11] offset:2560
	global_atomic_add v149, v211, s[10:11] offset:2816
	global_atomic_add v149, v211, s[10:11] offset:3072
	global_atomic_add v149, v211, s[10:11] offset:3328
	global_atomic_add v149, v211, s[10:11] offset:3584
	global_atomic_add v149, v211, s[10:11] offset:3840
	s_lshl_b32 s4, s22, 2
	s_add_u32 s4, s2, s4
	s_addc_u32 s5, s3, 0
	s_add_u32 s4, s4, 0x2400
	s_addc_u32 s5, s5, 0
	v_mov_b64_e32 v[0:1], s[4:5]
	s_mov_b64 s[6:7], exec
